# stack11 + prefetch pass before W_in stage_rstd loop: all 4 iterations ssq row and bgate addresses touched with one dword load each before the serialized load-wait-compute loop
# speedup vs baseline: 1.0002x; 1.0002x over previous
; #define LAS __attribute__((address_space(3)))
; __device__ __forceinline__ float sum4(f32x4 a) { return (a[0] + a[1]) + (a[2] + a[3]); }
;     __host__ __device__ bool next(int i, Unit& u) const {
;         const int t = i / NZ; u.pz = i - t * NZ; u.ord = i;
;         const long L = (long)t * G + c; if (L >= nwg) return false;
;         int wgid = (int)L; { const int q = nwg / NXCD, r = nwg % NXCD, xcd = wgid % NXCD, off = wgid / NXCD; wgid = (xcd < r ? xcd * (q + 1) : r * (q + 1) + (xcd - r) * q) + off; }
;         const int nig = WGM * nN, gid = wgid / nig, fm = gid * WGM, gsz = (nM - fm) < WGM ? (nM - fm) : WGM;
;         u.pm = fm + ((wgid % nig) % gsz); u.pn = (wgid % nig) / gsz; return true;
; __device__ __forceinline__ void stage_rstd(LAS unsigned char* lds, const pg8::StaticOrder& S, const float* ssq, const float* bgate, int tid) {
;     LAS float* rs = (LAS float*)(lds + SPARE_RS); LAS float* bg = (LAS float*)(lds + SPARE_BG);
;     for (int e = tid; e < 7 * 256; e += 512) { const int i = e >> 8, r = e & 255; pg8::Unit u;
;         if (S.next(i, u)) { const f32x4* sp = (const f32x4*)(ssq + (size_t)(u.pm * 256 + r) * 16); const f32x4 a = sp[0], b = sp[1], c = sp[2], d = sp[3];
;             rs[e] = rsqrtf(((sum4(a) + sum4(b)) + (sum4(c) + sum4(d))) * (1.0f / 1024.0f) + EPS);
;             if (bgate) bg[e] = (u.pn >= 12 && u.pn < 24) ? bgate[256 * (u.pn - 12) + r] : 0.f; } }
.LBB0_175:
	v_readlane_b32 s0, v254, 30
	s_or_b32 s2, s0, 1
	v_readlane_b32 s1, v254, 31
	s_cmp_le_i32 s30, s2
	s_cselect_b64 s[0:1], -1, 0
	s_cmp_lt_i32 s2, s31
	s_cselect_b64 s[2:3], -1, 0
	s_and_b64 s[94:95], s[0:1], s[2:3]
	v_readlane_b32 s0, v254, 27
	s_lshl_b32 s44, s0, 6
	v_readlane_b32 s48, v251, 19
	s_lshl_b32 s46, s0, 7
	s_lshl_b64 s[0:1], s[44:45], 2
	v_readlane_b32 s54, v251, 25
	s_mov_b64 s[20:21], s[28:29]
	v_readlane_b32 s55, v251, 26
	s_add_u32 s92, s54, s0
	s_mov_b64 s[22:23], s[30:31]
	s_addc_u32 s93, s55, s1
	s_andn2_b64 vcc, exec, s[94:95]
	s_mov_b32 s47, s45
	v_readlane_b32 s49, v251, 20
	v_readlane_b32 s50, v251, 21
	v_readlane_b32 s51, v251, 22
	v_readlane_b32 s52, v251, 23
	v_readlane_b32 s53, v251, 24
	v_readlane_b32 s56, v251, 27
	v_readlane_b32 s57, v251, 28
	v_readlane_b32 s58, v251, 29
	v_readlane_b32 s59, v251, 30
	v_readlane_b32 s60, v251, 31
	v_readlane_b32 s61, v251, 32
	v_readlane_b32 s62, v251, 33
	v_readlane_b32 s63, v251, 34
	s_cbranch_vccnz .LBB0_293
	s_mov_b64 s[0:1], 0
	s_add_u32 s2, s20, s0
	v_readlane_b32 s0, v251, 2
	v_mbcnt_lo_u32_b32 v0, -1, 0
	v_mbcnt_hi_u32_b32 v0, -1, v0
	s_addc_u32 s3, s21, s1
	s_waitcnt vmcnt(0)
	v_add_u32_e32 v4, s0, v0
	s_movk_i32 s0, 0x700
	s_nop 0
	v_cmp_gt_i32_e32 vcc, s0, v4
	s_and_saveexec_b64 s[4:5], vcc
	s_cbranch_execz .LBB0_186
	v_readlane_b32 s0, v254, 27
	s_add_u32 s10, s2, 0x100000
	s_mul_i32 s44, s0, 0xc00
	v_readlane_b32 s48, v251, 3
	s_addc_u32 s11, s3, 0
	s_lshl_b64 s[0:1], s[44:45], 2
	v_readlane_b32 s56, v251, 11
	v_readlane_b32 s57, v251, 12
	s_add_u32 s20, s56, s0
	v_and_b32_e32 v5, 0xff, v4
	v_readlane_b32 s0, v254, 11
	s_addc_u32 s21, s57, s1
	s_waitcnt lgkmcnt(0)
	v_or_b32_e32 v6, 0xfffff400, v5
	v_lshl_add_u32 v7, v4, 2, s0
	s_mov_b64 s[22:23], 0
	v_readlane_b32 s49, v251, 4
	v_readlane_b32 s50, v251, 5
	v_readlane_b32 s51, v251, 6
	v_readlane_b32 s52, v251, 7
	v_readlane_b32 s53, v251, 8
	v_readlane_b32 s54, v251, 9
	v_readlane_b32 s55, v251, 10
	v_readlane_b32 s58, v251, 13
	v_readlane_b32 s59, v251, 14
	v_readlane_b32 s60, v251, 15
	v_readlane_b32 s61, v251, 16
	v_readlane_b32 s62, v251, 17
	v_readlane_b32 s63, v251, 18
	s_mov_b64 s[6:7], exec
	v_mov_b32_e32 v25, v4
	v_readlane_b32 s0, v254, 3
	v_readlane_b32 s1, v254, 4
	v_ashrrev_i32_e32 v0, 8, v25
	s_nop 0
	v_mov_b64_e32 v[2:3], s[0:1]
	v_mad_i64_i32 v[2:3], s[0:1], v0, s26, v[2:3]
	s_mov_b64 s[0:1], 0x6c0
	s_nop 0
	v_cmp_gt_i64_e32 vcc, s[0:1], v[2:3]
	s_and_b64 exec, exec, vcc
	v_ashrrev_i32_e32 v0, 31, v2
	v_lshrrev_b32_e32 v0, 29, v0
	v_add_u32_e32 v0, v2, v0
	v_ashrrev_i32_e32 v3, 3, v0
	v_and_b32_e32 v0, -8, v0
	v_sub_u32_e32 v0, v2, v0
	v_cmp_gt_i32_e64 s[0:1], 0, v0
	v_mov_b32_e32 v2, 0xd8
	v_mov_b32_e32 v8, 0xd9
	v_cndmask_b32_e64 v2, v2, v8, s[0:1]
	v_mul_lo_u32 v0, v0, v2
	v_add_u32_e32 v0, v0, v3
	s_mov_b32 s0, 0x4bda12f7
	v_mul_hi_i32 v2, v0, s0
	v_lshrrev_b32_e32 v3, 31, v2
	v_ashrrev_i32_e32 v2, 6, v2
	v_add_u32_e32 v2, v2, v3
	v_lshlrev_b32_e32 v3, 3, v2
	v_sub_u32_e32 v8, 64, v3
	v_min_i32_e32 v9, 8, v8
	v_sub_u32_e32 v8, 0, v9
	v_max_i32_e32 v8, v9, v8
	v_cvt_f32_u32_e32 v10, v8
	s_movk_i32 s0, 0xd8
	v_mul_lo_u32 v2, v2, s0
	v_sub_u32_e32 v12, 0, v8
	v_rcp_iflag_f32_e32 v10, v10
	v_sub_u32_e32 v0, v0, v2
	v_sub_u32_e32 v11, 0, v0
	v_max_i32_e32 v11, v0, v11
	v_mul_f32_e32 v10, 0x4f7ffffe, v10
	v_cvt_u32_f32_e32 v10, v10
	v_xor_b32_e32 v2, v0, v9
	v_ashrrev_i32_e32 v2, 31, v2
	v_mul_lo_u32 v12, v12, v10
	v_mul_hi_u32 v12, v10, v12
	v_add_u32_e32 v10, v10, v12
	v_mul_hi_u32 v10, v11, v10
	v_mul_lo_u32 v12, v10, v8
	v_sub_u32_e32 v11, v11, v12
	v_add_u32_e32 v12, 1, v10
	v_cmp_ge_u32_e64 s[0:1], v11, v8
	s_nop 1
	v_cndmask_b32_e64 v10, v10, v12, s[0:1]
	v_sub_u32_e32 v12, v11, v8
	v_cndmask_b32_e64 v11, v11, v12, s[0:1]
	v_add_u32_e32 v12, 1, v10
	v_cmp_ge_u32_e64 s[0:1], v11, v8
	s_nop 1
	v_cndmask_b32_e64 v8, v10, v12, s[0:1]
	v_xor_b32_e32 v8, v8, v2
	v_sub_u32_e32 v8, v8, v2
	v_mul_lo_u32 v2, v8, v9
	v_sub_u32_e32 v0, v0, v2
	v_add_u32_e32 v9, v3, v0
	v_lshl_or_b32 v2, v9, 8, v5
	v_ashrrev_i32_e32 v3, 31, v2
	v_lshlrev_b64 v[2:3], 6, v[2:3]
	v_lshl_add_u64 v[2:3], s[10:11], 0, v[2:3]
	global_load_dword v13, v[2:3], off
	v_add_u32_e32 v0, -12, v8
	v_cmp_gt_u32_e32 vcc, 12, v0
	s_and_b64 exec, exec, vcc
	v_lshl_add_u32 v0, v8, 8, v6
	v_lshl_add_u64 v[2:3], v[0:1], 2, s[20:21]
	global_load_dword v14, v[2:3], off
	v_add_u32_e32 v25, 0x200, v25
	s_mov_b64 exec, s[6:7]
	s_movk_i32 s0, 0x700
	v_cmp_gt_i32_e32 vcc, s0, v25
	s_and_b64 exec, exec, vcc
	v_readlane_b32 s0, v254, 3
	v_readlane_b32 s1, v254, 4
	v_ashrrev_i32_e32 v0, 8, v25
	s_nop 0
	v_mov_b64_e32 v[2:3], s[0:1]
	v_mad_i64_i32 v[2:3], s[0:1], v0, s26, v[2:3]
	s_mov_b64 s[0:1], 0x6c0
	s_nop 0
	v_cmp_gt_i64_e32 vcc, s[0:1], v[2:3]
	s_and_b64 exec, exec, vcc
	v_ashrrev_i32_e32 v0, 31, v2
	v_lshrrev_b32_e32 v0, 29, v0
	v_add_u32_e32 v0, v2, v0
	v_ashrrev_i32_e32 v3, 3, v0
	v_and_b32_e32 v0, -8, v0
	v_sub_u32_e32 v0, v2, v0
	v_cmp_gt_i32_e64 s[0:1], 0, v0
	v_mov_b32_e32 v2, 0xd8
	v_mov_b32_e32 v8, 0xd9
	v_cndmask_b32_e64 v2, v2, v8, s[0:1]
	v_mul_lo_u32 v0, v0, v2
	v_add_u32_e32 v0, v0, v3
	s_mov_b32 s0, 0x4bda12f7
	v_mul_hi_i32 v2, v0, s0
	v_lshrrev_b32_e32 v3, 31, v2
	v_ashrrev_i32_e32 v2, 6, v2
	v_add_u32_e32 v2, v2, v3
	v_lshlrev_b32_e32 v3, 3, v2
	v_sub_u32_e32 v8, 64, v3
	v_min_i32_e32 v9, 8, v8
	v_sub_u32_e32 v8, 0, v9
	v_max_i32_e32 v8, v9, v8
	v_cvt_f32_u32_e32 v10, v8
	s_movk_i32 s0, 0xd8
	v_mul_lo_u32 v2, v2, s0
	v_sub_u32_e32 v12, 0, v8
	v_rcp_iflag_f32_e32 v10, v10
	v_sub_u32_e32 v0, v0, v2
	v_sub_u32_e32 v11, 0, v0
	v_max_i32_e32 v11, v0, v11
	v_mul_f32_e32 v10, 0x4f7ffffe, v10
	v_cvt_u32_f32_e32 v10, v10
; __device__ __forceinline__ float sum4(f32x4 a) { return (a[0] + a[1]) + (a[2] + a[3]); }
;     __host__ __device__ bool next(int i, Unit& u) const {
;         const int t = i / NZ; u.pz = i - t * NZ; u.ord = i;
;         const long L = (long)t * G + c; if (L >= nwg) return false;
;         int wgid = (int)L; { const int q = nwg / NXCD, r = nwg % NXCD, xcd = wgid % NXCD, off = wgid / NXCD; wgid = (xcd < r ? xcd * (q + 1) : r * (q + 1) + (xcd - r) * q) + off; }
;         const int nig = WGM * nN, gid = wgid / nig, fm = gid * WGM, gsz = (nM - fm) < WGM ? (nM - fm) : WGM;
;         u.pm = fm + ((wgid % nig) % gsz); u.pn = (wgid % nig) / gsz; return true;
; __device__ __forceinline__ void stage_rstd(LAS unsigned char* lds, const pg8::StaticOrder& S, const float* ssq, const float* bgate, int tid) {
;     ...
;     for (int e = tid; e < 7 * 256; e += 512) { const int i = e >> 8, r = e & 255; pg8::Unit u;
;         if (S.next(i, u)) { const f32x4* sp = (const f32x4*)(ssq + (size_t)(u.pm * 256 + r) * 16); const f32x4 a = sp[0], b = sp[1], c = sp[2], d = sp[3];
;             rs[e] = rsqrtf(((sum4(a) + sum4(b)) + (sum4(c) + sum4(d))) * (1.0f / 1024.0f) + EPS);
;             if (bgate) bg[e] = (u.pn >= 12 && u.pn < 24) ? bgate[256 * (u.pn - 12) + r] : 0.f; } }
	v_xor_b32_e32 v2, v0, v9
	v_ashrrev_i32_e32 v2, 31, v2
	v_mul_lo_u32 v12, v12, v10
	v_mul_hi_u32 v12, v10, v12
	v_add_u32_e32 v10, v10, v12
	v_mul_hi_u32 v10, v11, v10
	v_mul_lo_u32 v12, v10, v8
	v_sub_u32_e32 v11, v11, v12
	v_add_u32_e32 v12, 1, v10
	v_cmp_ge_u32_e64 s[0:1], v11, v8
	s_nop 1
	v_cndmask_b32_e64 v10, v10, v12, s[0:1]
	v_sub_u32_e32 v12, v11, v8
	v_cndmask_b32_e64 v11, v11, v12, s[0:1]
	v_add_u32_e32 v12, 1, v10
	v_cmp_ge_u32_e64 s[0:1], v11, v8
	s_nop 1
	v_cndmask_b32_e64 v8, v10, v12, s[0:1]
	v_xor_b32_e32 v8, v8, v2
	v_sub_u32_e32 v8, v8, v2
	v_mul_lo_u32 v2, v8, v9
	v_sub_u32_e32 v0, v0, v2
	v_add_u32_e32 v9, v3, v0
	v_lshl_or_b32 v2, v9, 8, v5
	v_ashrrev_i32_e32 v3, 31, v2
	v_lshlrev_b64 v[2:3], 6, v[2:3]
	v_lshl_add_u64 v[2:3], s[10:11], 0, v[2:3]
	global_load_dword v13, v[2:3], off
	v_add_u32_e32 v0, -12, v8
	v_cmp_gt_u32_e32 vcc, 12, v0
	s_and_b64 exec, exec, vcc
	v_lshl_add_u32 v0, v8, 8, v6
	v_lshl_add_u64 v[2:3], v[0:1], 2, s[20:21]
	global_load_dword v14, v[2:3], off
	v_add_u32_e32 v25, 0x200, v25
	s_mov_b64 exec, s[6:7]
	s_movk_i32 s0, 0x700
	v_cmp_gt_i32_e32 vcc, s0, v25
	s_and_b64 exec, exec, vcc
	v_readlane_b32 s0, v254, 3
	v_readlane_b32 s1, v254, 4
	v_ashrrev_i32_e32 v0, 8, v25
	s_nop 0
	v_mov_b64_e32 v[2:3], s[0:1]
	v_mad_i64_i32 v[2:3], s[0:1], v0, s26, v[2:3]
	s_mov_b64 s[0:1], 0x6c0
	s_nop 0
	v_cmp_gt_i64_e32 vcc, s[0:1], v[2:3]
	s_and_b64 exec, exec, vcc
	v_ashrrev_i32_e32 v0, 31, v2
	v_lshrrev_b32_e32 v0, 29, v0
	v_add_u32_e32 v0, v2, v0
	v_ashrrev_i32_e32 v3, 3, v0
	v_and_b32_e32 v0, -8, v0
	v_sub_u32_e32 v0, v2, v0
	v_cmp_gt_i32_e64 s[0:1], 0, v0
	v_mov_b32_e32 v2, 0xd8
	v_mov_b32_e32 v8, 0xd9
	v_cndmask_b32_e64 v2, v2, v8, s[0:1]
	v_mul_lo_u32 v0, v0, v2
	v_add_u32_e32 v0, v0, v3
	s_mov_b32 s0, 0x4bda12f7
	v_mul_hi_i32 v2, v0, s0
	v_lshrrev_b32_e32 v3, 31, v2
	v_ashrrev_i32_e32 v2, 6, v2
	v_add_u32_e32 v2, v2, v3
	v_lshlrev_b32_e32 v3, 3, v2
	v_sub_u32_e32 v8, 64, v3
	v_min_i32_e32 v9, 8, v8
	v_sub_u32_e32 v8, 0, v9
	v_max_i32_e32 v8, v9, v8
	v_cvt_f32_u32_e32 v10, v8
	s_movk_i32 s0, 0xd8
	v_mul_lo_u32 v2, v2, s0
	v_sub_u32_e32 v12, 0, v8
	v_rcp_iflag_f32_e32 v10, v10
	v_sub_u32_e32 v0, v0, v2
	v_sub_u32_e32 v11, 0, v0
	v_max_i32_e32 v11, v0, v11
	v_mul_f32_e32 v10, 0x4f7ffffe, v10
	v_cvt_u32_f32_e32 v10, v10
	v_xor_b32_e32 v2, v0, v9
	v_ashrrev_i32_e32 v2, 31, v2
	v_mul_lo_u32 v12, v12, v10
	v_mul_hi_u32 v12, v10, v12
	v_add_u32_e32 v10, v10, v12
	v_mul_hi_u32 v10, v11, v10
	v_mul_lo_u32 v12, v10, v8
	v_sub_u32_e32 v11, v11, v12
	v_add_u32_e32 v12, 1, v10
	v_cmp_ge_u32_e64 s[0:1], v11, v8
	s_nop 1
	v_cndmask_b32_e64 v10, v10, v12, s[0:1]
	v_sub_u32_e32 v12, v11, v8
	v_cndmask_b32_e64 v11, v11, v12, s[0:1]
	v_add_u32_e32 v12, 1, v10
	v_cmp_ge_u32_e64 s[0:1], v11, v8
	s_nop 1
	v_cndmask_b32_e64 v8, v10, v12, s[0:1]
	v_xor_b32_e32 v8, v8, v2
	v_sub_u32_e32 v8, v8, v2
	v_mul_lo_u32 v2, v8, v9
	v_sub_u32_e32 v0, v0, v2
	v_add_u32_e32 v9, v3, v0
	v_lshl_or_b32 v2, v9, 8, v5
	v_ashrrev_i32_e32 v3, 31, v2
	v_lshlrev_b64 v[2:3], 6, v[2:3]
	v_lshl_add_u64 v[2:3], s[10:11], 0, v[2:3]
	global_load_dword v13, v[2:3], off
	v_add_u32_e32 v0, -12, v8
	v_cmp_gt_u32_e32 vcc, 12, v0
	s_and_b64 exec, exec, vcc
	v_lshl_add_u32 v0, v8, 8, v6
	v_lshl_add_u64 v[2:3], v[0:1], 2, s[20:21]
	global_load_dword v14, v[2:3], off
	v_add_u32_e32 v25, 0x200, v25
	s_mov_b64 exec, s[6:7]
	s_movk_i32 s0, 0x700
	v_cmp_gt_i32_e32 vcc, s0, v25
	s_and_b64 exec, exec, vcc
	v_readlane_b32 s0, v254, 3
	v_readlane_b32 s1, v254, 4
	v_ashrrev_i32_e32 v0, 8, v25
	s_nop 0
	v_mov_b64_e32 v[2:3], s[0:1]
	v_mad_i64_i32 v[2:3], s[0:1], v0, s26, v[2:3]
	s_mov_b64 s[0:1], 0x6c0
	s_nop 0
	v_cmp_gt_i64_e32 vcc, s[0:1], v[2:3]
	s_and_b64 exec, exec, vcc
	v_ashrrev_i32_e32 v0, 31, v2
	v_lshrrev_b32_e32 v0, 29, v0
	v_add_u32_e32 v0, v2, v0
	v_ashrrev_i32_e32 v3, 3, v0
	v_and_b32_e32 v0, -8, v0
	v_sub_u32_e32 v0, v2, v0
	v_cmp_gt_i32_e64 s[0:1], 0, v0
	v_mov_b32_e32 v2, 0xd8
	v_mov_b32_e32 v8, 0xd9
	v_cndmask_b32_e64 v2, v2, v8, s[0:1]
	v_mul_lo_u32 v0, v0, v2
	v_add_u32_e32 v0, v0, v3
	s_mov_b32 s0, 0x4bda12f7
	v_mul_hi_i32 v2, v0, s0
	v_lshrrev_b32_e32 v3, 31, v2
	v_ashrrev_i32_e32 v2, 6, v2
	v_add_u32_e32 v2, v2, v3
	v_lshlrev_b32_e32 v3, 3, v2
	v_sub_u32_e32 v8, 64, v3
	v_min_i32_e32 v9, 8, v8
	v_sub_u32_e32 v8, 0, v9
	v_max_i32_e32 v8, v9, v8
	v_cvt_f32_u32_e32 v10, v8
	s_movk_i32 s0, 0xd8
	v_mul_lo_u32 v2, v2, s0
	v_sub_u32_e32 v12, 0, v8
	v_rcp_iflag_f32_e32 v10, v10
	v_sub_u32_e32 v0, v0, v2
	v_sub_u32_e32 v11, 0, v0
	v_max_i32_e32 v11, v0, v11
	v_mul_f32_e32 v10, 0x4f7ffffe, v10
	v_cvt_u32_f32_e32 v10, v10
	v_xor_b32_e32 v2, v0, v9
	v_ashrrev_i32_e32 v2, 31, v2
	v_mul_lo_u32 v12, v12, v10
	v_mul_hi_u32 v12, v10, v12
	v_add_u32_e32 v10, v10, v12
	v_mul_hi_u32 v10, v11, v10
	v_mul_lo_u32 v12, v10, v8
	v_sub_u32_e32 v11, v11, v12
	v_add_u32_e32 v12, 1, v10
	v_cmp_ge_u32_e64 s[0:1], v11, v8
	s_nop 1
	v_cndmask_b32_e64 v10, v10, v12, s[0:1]
	v_sub_u32_e32 v12, v11, v8
	v_cndmask_b32_e64 v11, v11, v12, s[0:1]
	v_add_u32_e32 v12, 1, v10
	v_cmp_ge_u32_e64 s[0:1], v11, v8
	s_nop 1
	v_cndmask_b32_e64 v8, v10, v12, s[0:1]
	v_xor_b32_e32 v8, v8, v2
	v_sub_u32_e32 v8, v8, v2
	v_mul_lo_u32 v2, v8, v9
	v_sub_u32_e32 v0, v0, v2
	v_add_u32_e32 v9, v3, v0
	v_lshl_or_b32 v2, v9, 8, v5
	v_ashrrev_i32_e32 v3, 31, v2
	v_lshlrev_b64 v[2:3], 6, v[2:3]
	v_lshl_add_u64 v[2:3], s[10:11], 0, v[2:3]
	global_load_dword v13, v[2:3], off
	v_add_u32_e32 v0, -12, v8
	v_cmp_gt_u32_e32 vcc, 12, v0
	s_and_b64 exec, exec, vcc
	v_lshl_add_u32 v0, v8, 8, v6
	v_lshl_add_u64 v[2:3], v[0:1], 2, s[20:21]
	global_load_dword v14, v[2:3], off
	s_mov_b64 exec, s[6:7]
	s_branch .LBB0_180
